# on top of previous: RWKV-7 chunk group-norm stage (P6) rewritten with the four 64-lane reductions interleaved (6-step DPP, same pairing order), plain v_rsq
# speedup vs baseline: 1.0014x; 1.0014x over previous
; DI bf16_t f2bf(float f) { return (bf16_t)(pack2(f, 0.f) & 0xFFFFu); }
; __device__ __forceinline__ void rwkv_chunked(unsigned char* smem, CP p, int L, int b, int h) {
;     ...
; #pragma unroll
;         for (int i = 0; i < 2; ++i) { const int t = wv * 2 + i;
;             const float y = YS[t * 64 + c]; const float s1_ = wave_sum(y), s2_ = wave_sum(y * y);
;             const float mean = s1_ * (1.0f / 64.0f); const float dlt = y - mean; const float var = fmaxf(s2_ * (1.0f / 64.0f) - mean * mean, 0.f);
;             float yn = dlt * rsqrtf(var + 64e-5f) * ln_w + ln_b; yn += bon[i] * VS[t * 64 + c];
;             obase[(size_t)(ch * 16 + t) * 512] = f2bf(yn * gv[i]); }
.LBB0_664:
	s_or_b64 exec, exec, vcc
	v_mov_b32_e32 v2, s20
	v_mov_b32_e32 v3, s21
	v_add_f32_e32 v2, s18, v2
	v_add_f32_e32 v3, s19, v3
	v_add_f32_e32 v8, v2, v3
	v_mov_b32_e32 v2, s12
	v_mov_b32_e32 v3, s13
	v_add_f32_e32 v2, s22, v2
	v_add_f32_e32 v3, s23, v3
	v_add_f32_e32 v11, v2, v3
	s_waitcnt lgkmcnt(0)
	s_barrier
	ds_read2st64_b32 v[2:3], v107 offset0:223 offset1:239
	ds_read2st64_b32 v[4:5], v108 offset0:223 offset1:239
	v_lshlrev_b32_e32 v0, 16, v100
	v_lshlrev_b32_e32 v10, 16, v101
	v_mov_b32_e32 v13, 0x3c800000
	s_waitcnt vmcnt(6)
	v_mov_b32_e32 v100, v110
	s_waitcnt vmcnt(0)
	v_mov_b32_e32 v101, v112
	s_waitcnt lgkmcnt(0)
	v_mul_f32_e32 v7, v2, v2
	v_mul_f32_e32 v9, v4, v4
	v_add_f32_dpp v6, v2, v2 quad_perm:[1,0,3,2] row_mask:0xf bank_mask:0xf bound_ctrl:1
	v_add_f32_dpp v12, v4, v4 quad_perm:[1,0,3,2] row_mask:0xf bank_mask:0xf bound_ctrl:1
	v_mov_b32_dpp v7, v7 quad_perm:[1,0,3,2] row_mask:0xf bank_mask:0xf bound_ctrl:1
	v_mov_b32_dpp v9, v9 quad_perm:[1,0,3,2] row_mask:0xf bank_mask:0xf bound_ctrl:1
	v_fmac_f32_e32 v7, v2, v2
	v_fmac_f32_e32 v9, v4, v4
	v_add_f32_dpp v6, v6, v6 quad_perm:[2,3,0,1] row_mask:0xf bank_mask:0xf bound_ctrl:1
	v_add_f32_dpp v12, v12, v12 quad_perm:[2,3,0,1] row_mask:0xf bank_mask:0xf bound_ctrl:1
	v_add_f32_dpp v7, v7, v7 quad_perm:[2,3,0,1] row_mask:0xf bank_mask:0xf bound_ctrl:1
	v_add_f32_dpp v9, v9, v9 quad_perm:[2,3,0,1] row_mask:0xf bank_mask:0xf bound_ctrl:1
	v_add_f32_dpp v6, v6, v6 row_half_mirror row_mask:0xf bank_mask:0xf bound_ctrl:1
	v_add_f32_dpp v12, v12, v12 row_half_mirror row_mask:0xf bank_mask:0xf bound_ctrl:1
	v_add_f32_dpp v7, v7, v7 row_half_mirror row_mask:0xf bank_mask:0xf bound_ctrl:1
	v_add_f32_dpp v9, v9, v9 row_half_mirror row_mask:0xf bank_mask:0xf bound_ctrl:1
	v_add_f32_dpp v6, v6, v6 row_mirror row_mask:0xf bank_mask:0xf bound_ctrl:1
	v_add_f32_dpp v12, v12, v12 row_mirror row_mask:0xf bank_mask:0xf bound_ctrl:1
	v_add_f32_dpp v7, v7, v7 row_mirror row_mask:0xf bank_mask:0xf bound_ctrl:1
	v_add_f32_dpp v9, v9, v9 row_mirror row_mask:0xf bank_mask:0xf bound_ctrl:1
	v_add_f32_dpp v6, v6, v6 row_bcast:15 row_mask:0xa bank_mask:0xf
	v_add_f32_dpp v12, v12, v12 row_bcast:15 row_mask:0xa bank_mask:0xf
	v_add_f32_dpp v7, v7, v7 row_bcast:15 row_mask:0xa bank_mask:0xf
	v_add_f32_dpp v9, v9, v9 row_bcast:15 row_mask:0xa bank_mask:0xf
	v_add_f32_dpp v6, v6, v6 row_bcast:31 row_mask:0xc bank_mask:0xf
	v_add_f32_dpp v12, v12, v12 row_bcast:31 row_mask:0xc bank_mask:0xf
	v_add_f32_dpp v7, v7, v7 row_bcast:31 row_mask:0xc bank_mask:0xf
	v_add_f32_dpp v9, v9, v9 row_bcast:31 row_mask:0xc bank_mask:0xf
	v_readlane_b32 s13, v6, 63
	v_readlane_b32 s15, v12, 63
	v_readlane_b32 s12, v7, 63
	v_readlane_b32 s14, v9, 63
	v_mul_f32_e32 v14, s13, v13
	v_mul_f32_e32 v34, s15, v13
	v_mul_f32_e32 v15, s12, v13
	v_mul_f32_e32 v35, s14, v13
	v_fma_f32 v15, -v14, v14, v15
	v_fma_f32 v35, -v34, v34, v35
	v_max_f32_e32 v15, 0, v15
	v_max_f32_e32 v35, 0, v35
	v_add_f32_e32 v15, 0x3a27c5ac, v15
	v_add_f32_e32 v35, 0x3a27c5ac, v35
	v_sub_f32_e32 v2, v2, v14
	v_sub_f32_e32 v4, v4, v34
	v_rsq_f32_e32 v15, v15
	v_rsq_f32_e32 v35, v35
	s_mov_b32 s16, 0x6ac8000
	v_add_co_u32_e32 v6, vcc, s16, v60
	v_mul_f32_e32 v2, v2, v15
	v_mul_f32_e32 v4, v4, v35
	v_addc_co_u32_e32 v7, vcc, 0, v61, vcc
	v_fma_f32 v2, v70, v2, v71
	v_fma_f32 v4, v70, v4, v71
	v_fmac_f32_e32 v2, v8, v3
	v_fmac_f32_e32 v4, v11, v5
	v_mul_f32_e32 v2, v2, v0
	v_mul_f32_e32 v4, v4, v10
	v_cvt_pk_bf16_f32 v2, v2, s0
	v_cvt_pk_bf16_f32 v4, v4, s0
	global_store_short v[6:7], v2, off
	global_store_short v[6:7], v4, off offset:1024
	s_mov_b64 s[12:13], 0x4000
	v_lshl_add_u64 v[52:53], v[52:53], 0, s[12:13]
	s_mov_b64 s[12:13], 0x42000
	v_lshl_add_u64 v[54:55], v[54:55], 0, s[12:13]
	s_mov_b64 s[12:13], 0x8000
	v_lshl_add_u64 v[56:57], v[56:57], 0, s[12:13]
	v_mov_b32_e32 v0, v109
	v_mov_b32_e32 v3, v111
	v_mov_b32_e32 v11, v113
	s_add_i32 s44, s44, 16
	s_cmpk_lg_i32 s44, 0x800
	s_cbranch_scc0 .LBB0_646
